# attention phase: static s_setprio 1 for waves 4-7
# baseline (speedup 1.0000x reference)
; __device__ __forceinline__ int lane_id() { return (int)__builtin_amdgcn_mbcnt_hi(~0u, __builtin_amdgcn_mbcnt_lo(~0u, 0u)); }
; __device__ __forceinline__ float wave_sum(float v) {
; #pragma unroll
;     for (int o = 1; o < 64; o <<= 1) v += __shfl_xor(v, o);
;     return v;
; }
; __device__ __forceinline__ float wave_max(float v) {
; #pragma unroll
;     for (int o = 1; o < 64; o <<= 1) v = fmaxf(v, __shfl_xor(v, o));
;     return v;
; }
; __global__ void __launch_bounds__(NWAVES * 64, 2) fwd(Args args) {
;     ...
;         unsigned char* wsp = ws; asm volatile("" : "+s"(wsp)); const unsigned char* tbl = wsp + WS_PTRS;
;         const float* ret_gn = ld_uptr(tbl, 4); const float* diff_qn = ld_uptr(tbl, 5); const float* diff_kn = ld_uptr(tbl, 6); const float* lq1 = ld_uptr(tbl, 7); const float* lk1 = ld_uptr(tbl, 8);
;         const float* lq2 = ld_uptr(tbl, 9); const float* lk2 = ld_uptr(tbl, 10); const float* subln = ld_uptr(tbl, 11);
;         bf16_t* Z = (bf16_t*)(wsp + WS_Z); bf16_t* MIX = (bf16_t*)(wsp + WS_MIX);
;         int lane2 = lane_id(); asm volatile("" : "+v"(lane2));
;         const float d1 = wave_sum(lq1[lane2] * lk1[lane2]), d2 = wave_sum(lq2[lane2] * lk2[lane2]);
;         float lam; { float lv = __expf(d1) - __expf(d2) + 0.2f; asm volatile("" : "+v"(lv)); lam = __uint_as_float(__builtin_amdgcn_readfirstlane(__float_as_uint(lv))); }
;         const float mq = wave_max(fabsf(diff_qn[lane2])), mk = wave_max(fabsf(diff_kn[lane2]));
;         float shift; { float sv = 11.541560327111707f * mq * mk; asm volatile("" : "+v"(sv)); shift = __uint_as_float(__builtin_amdgcn_readfirstlane(__float_as_uint(sv))); }
;         for (int pi = vcu; pi < 256; pi += G) {
.LBB0_561:
	s_cmp_lt_i32 s82, 3
	s_cselect_b64 s[2:3], -1, 0
	v_writelane_b32 v254, s2, 2
	s_and_b64 s[0:1], s[2:3], s[0:1]
	s_andn2_b64 vcc, exec, s[0:1]
	v_writelane_b32 v254, s3, 3
	s_cbranch_vccnz .LBB0_654
	v_writelane_b32 v254, s96, 4
	v_mov_b32_e32 v181, 0
	v_mbcnt_lo_u32_b32 v13, -1, 0
	v_writelane_b32 v254, s97, 5
	v_writelane_b32 v254, s94, 6
	v_writelane_b32 v254, s93, 7
	v_writelane_b32 v254, s92, 8
	v_writelane_b32 v254, s90, 9
	v_mbcnt_hi_u32_b32 v183, -1, v13
	v_mov_b32_e32 v12, 0x20000
	v_writelane_b32 v254, s91, 10
	v_writelane_b32 v254, s87, 11
	v_writelane_b32 v254, s88, 12
	v_mov_b32_e32 v16, v183
	s_mov_b32 s27, 0
	v_writelane_b32 v254, s89, 13
	v_writelane_b32 v254, s86, 14
	v_writelane_b32 v254, s84, 15
	s_nop 1
	v_writelane_b32 v254, s85, 16
	v_writelane_b32 v254, s79, 17
	v_writelane_b32 v254, s77, 18
	v_writelane_b32 v254, s80, 19
	s_mov_b64 s[0:1], s[80:81]
	s_add_u32 s2, s0, 0x20020
	s_addc_u32 s3, s1, 0
	global_load_dwordx4 v[0:3], v181, s[2:3] offset:16
	global_load_dwordx4 v[4:7], v181, s[2:3] offset:32
	global_load_dwordx4 v[8:11], v181, s[2:3] offset:48
	v_writelane_b32 v254, s81, 20
	global_load_dwordx4 v[12:15], v12, s[0:1] offset:32
	v_writelane_b32 v254, s82, 21
	v_ashrrev_i32_e32 v17, 31, v16
	v_lshlrev_b64 v[16:17], 2, v[16:17]
	v_writelane_b32 v254, s83, 22
	s_cmpk_gt_i32 s95, 0xff
	s_waitcnt vmcnt(0)
	v_readfirstlane_b32 s3, v3
	v_readfirstlane_b32 s2, v2
	v_readfirstlane_b32 s5, v5
	v_readfirstlane_b32 s4, v4
	v_readfirstlane_b32 s7, v7
	v_readfirstlane_b32 s6, v6
	v_readfirstlane_b32 s9, v9
	v_readfirstlane_b32 s8, v8
	v_lshl_add_u64 v[2:3], s[2:3], 0, v[16:17]
	v_lshl_add_u64 v[4:5], s[4:5], 0, v[16:17]
	v_lshl_add_u64 v[6:7], s[6:7], 0, v[16:17]
	v_lshl_add_u64 v[8:9], s[8:9], 0, v[16:17]
	flat_load_dword v18, v[2:3]
	flat_load_dword v19, v[4:5]
	flat_load_dword v20, v[6:7]
	flat_load_dword v21, v[8:9]
	v_and_b32_e32 v2, 64, v183
	v_xor_b32_e32 v3, 1, v183
	v_add_u32_e32 v2, 64, v2
	v_cmp_lt_i32_e32 vcc, v3, v2
	v_xor_b32_e32 v4, 2, v183
	v_xor_b32_e32 v5, 4, v183
	v_cndmask_b32_e32 v3, v183, v3, vcc
	v_lshlrev_b32_e32 v9, 2, v3
	v_cmp_lt_i32_e32 vcc, v4, v2
	v_xor_b32_e32 v6, 8, v183
	v_xor_b32_e32 v7, 16, v183
	v_cndmask_b32_e32 v4, v183, v4, vcc
	v_lshlrev_b32_e32 v4, 2, v4
	v_cmp_lt_i32_e32 vcc, v5, v2
	v_xor_b32_e32 v8, 32, v183
	v_readfirstlane_b32 s5, v1
	v_cndmask_b32_e32 v5, v183, v5, vcc
	v_lshlrev_b32_e32 v5, 2, v5
	v_cmp_lt_i32_e32 vcc, v6, v2
	v_readfirstlane_b32 s3, v15
	v_readfirstlane_b32 s2, v14
	v_cndmask_b32_e32 v6, v183, v6, vcc
	v_lshlrev_b32_e32 v6, 2, v6
	v_cmp_lt_i32_e32 vcc, v7, v2
	v_readfirstlane_b32 s4, v0
	v_readfirstlane_b32 s85, v11
	v_cndmask_b32_e32 v7, v183, v7, vcc
	v_lshlrev_b32_e32 v7, 2, v7
	v_cmp_lt_i32_e32 vcc, v8, v2
	v_readfirstlane_b32 s84, v10
	s_waitcnt vmcnt(0) lgkmcnt(0)
	v_mul_f32_e32 v3, v18, v19
	ds_bpermute_b32 v3, v9, v3
	v_mul_f32_e32 v22, v20, v21
	ds_bpermute_b32 v22, v9, v22
	v_cndmask_b32_e32 v2, v183, v8, vcc
	v_lshlrev_b32_e32 v8, 2, v2
	s_waitcnt lgkmcnt(1)
	v_fmac_f32_e32 v3, v18, v19
	ds_bpermute_b32 v18, v4, v3
	s_waitcnt lgkmcnt(1)
	v_fmac_f32_e32 v22, v20, v21
	ds_bpermute_b32 v19, v4, v22
	s_waitcnt lgkmcnt(1)
	v_add_f32_e32 v3, v3, v18
	s_waitcnt lgkmcnt(0)
	v_add_f32_e32 v18, v22, v19
	ds_bpermute_b32 v19, v5, v3
	ds_bpermute_b32 v20, v5, v18
	s_waitcnt lgkmcnt(1)
	v_add_f32_e32 v3, v3, v19
	s_waitcnt lgkmcnt(0)
	v_add_f32_e32 v18, v18, v20
	ds_bpermute_b32 v19, v6, v3
	ds_bpermute_b32 v20, v6, v18
	s_waitcnt lgkmcnt(1)
	v_add_f32_e32 v3, v3, v19
	s_waitcnt lgkmcnt(0)
	v_add_f32_e32 v18, v18, v20
	ds_bpermute_b32 v19, v7, v3
	ds_bpermute_b32 v20, v7, v18
	s_waitcnt lgkmcnt(1)
	v_add_f32_e32 v2, v3, v19
	s_waitcnt lgkmcnt(0)
	v_add_f32_e32 v3, v18, v20
	ds_bpermute_b32 v18, v8, v2
	ds_bpermute_b32 v19, v8, v3
	s_waitcnt lgkmcnt(1)
	v_add_f32_e32 v1, v2, v18
	s_waitcnt lgkmcnt(0)
	v_add_f32_e32 v2, v3, v19
	v_mul_f32_e32 v1, 0x3fb8aa3b, v1
	v_mul_f32_e32 v2, 0x3fb8aa3b, v2
	v_exp_f32_e32 v14, v1
	v_exp_f32_e32 v15, v2
	v_lshl_add_u64 v[0:1], s[2:3], 0, v[16:17]
	v_lshl_add_u64 v[2:3], s[4:5], 0, v[16:17]
	v_readfirstlane_b32 s2, v13
	v_sub_f32_e32 v14, v14, v15
	v_add_f32_e32 v14, 0x3e4ccccd, v14
	flat_load_dword v15, v[0:1]
	flat_load_dword v16, v[2:3]
	v_writelane_b32 v254, s2, 23
	v_readfirstlane_b32 s2, v12
	v_readfirstlane_b32 s28, v14
	s_waitcnt vmcnt(0) lgkmcnt(0)
	v_and_b32_e32 v0, 0x7fffffff, v15
	v_and_b32_e32 v1, 0x7fffffff, v16
	ds_bpermute_b32 v0, v9, v0
	ds_bpermute_b32 v1, v9, v1
	v_max_f32_e64 v2, |v15|, |v15|
	v_max_f32_e64 v3, |v16|, |v16|
	v_writelane_b32 v254, s2, 24
	s_waitcnt lgkmcnt(1)
	v_max_f32_e32 v0, v0, v0
	s_waitcnt lgkmcnt(0)
	v_max_f32_e32 v1, v1, v1
	v_max_f32_e32 v0, v2, v0
	v_max_f32_e32 v1, v3, v1
	ds_bpermute_b32 v2, v4, v0
	ds_bpermute_b32 v3, v4, v1
	s_waitcnt lgkmcnt(1)
	v_max_f32_e32 v2, v2, v2
	s_waitcnt lgkmcnt(0)
	v_max_f32_e32 v3, v3, v3
	v_max_f32_e32 v0, v0, v2
	v_max_f32_e32 v1, v1, v3
	ds_bpermute_b32 v2, v5, v0
	ds_bpermute_b32 v3, v5, v1
	s_waitcnt lgkmcnt(1)
	v_max_f32_e32 v2, v2, v2
	s_waitcnt lgkmcnt(0)
	v_max_f32_e32 v3, v3, v3
	v_max_f32_e32 v0, v0, v2
	v_max_f32_e32 v1, v1, v3
	ds_bpermute_b32 v2, v6, v0
	ds_bpermute_b32 v3, v6, v1
	s_waitcnt lgkmcnt(1)
	v_max_f32_e32 v2, v2, v2
	s_waitcnt lgkmcnt(0)
	v_max_f32_e32 v3, v3, v3
	v_max_f32_e32 v0, v0, v2
	v_max_f32_e32 v1, v1, v3
	ds_bpermute_b32 v2, v7, v0
	ds_bpermute_b32 v3, v7, v1
	s_waitcnt lgkmcnt(1)
	v_max_f32_e32 v2, v2, v2
	s_waitcnt lgkmcnt(0)
	v_max_f32_e32 v3, v3, v3
	v_max_f32_e32 v0, v0, v2
	v_max_f32_e32 v1, v1, v3
	ds_bpermute_b32 v2, v8, v0
	ds_bpermute_b32 v3, v8, v1
	s_waitcnt lgkmcnt(1)
	v_max_f32_e32 v2, v2, v2
	s_waitcnt lgkmcnt(0)
	v_max_f32_e32 v3, v3, v3
	v_max_f32_e32 v0, v0, v2
	v_max_f32_e32 v1, v1, v3
	v_mul_f32_e32 v0, 0x4138aa3b, v0
	v_mul_f32_e32 v0, v0, v1
	s_nop 0
	v_readfirstlane_b32 s2, v0
	s_cbranch_scc1 .LBB0_653
	s_add_u32 s30, s0, 0x5300000
	s_addc_u32 s31, s1, 0
	s_add_u32 s88, s0, 0x2f00000
	s_addc_u32 s89, s1, 0
	s_cmp_ge_u32 s60, 4
	s_cbranch_scc0 .Lp2prio_skip
	s_setprio 1
; __global__ void __launch_bounds__(NWAVES * 64, 2) fwd(Args args) {
;     ...
;         for (int pi = vcu; pi < 256; pi += G) {
;             const int bh = pi >> 3, tp = pi & 7, b = bh >> 3, h = bh & 7;
;             attn_item<true>(lds, Z, MIX, b, h, 15 - tp, lam, shift, subln, 0, wid, 0);
.Lp2prio_skip:
	s_lshl_b32 s29, s60, 4
	s_lshl_b32 s34, s60, 3
	s_lshl_b32 s35, s60, 2
	s_add_i32 s90, s33, 0
	v_sub_f32_e64 v0, 0, s2
	s_add_u32 s2, s0, 0x54c2800
	v_writelane_b32 v254, s2, 25
	s_addc_u32 s2, s1, 0
	v_writelane_b32 v254, s2, 26
	s_lshl_b32 s2, s95, 5
	s_lshl_b32 s3, s78, 5
	v_writelane_b32 v254, s3, 27
	s_add_u32 s3, s0, 0x54c0800
	v_writelane_b32 v254, s3, 28
	s_addc_u32 s3, s1, 0
	v_writelane_b32 v254, s3, 29
	s_add_u32 s0, s0, 0x54c0400
	v_writelane_b32 v254, s0, 30
	s_addc_u32 s0, s1, 0
	v_writelane_b32 v254, s0, 31
	v_writelane_b32 v254, s78, 32
	v_writelane_b32 v254, s66, 33
	v_writelane_b32 v254, s84, 34
	s_add_i32 s17, s90, 0x2000
	s_add_i32 s38, s90, 0x6000
	v_writelane_b32 v254, s85, 35
	v_writelane_b32 v254, s28, 36
	v_writelane_b32 v254, s30, 37
	s_add_i32 s39, s90, 0x8000
	s_add_i32 s18, s90, 0xa000
	v_writelane_b32 v254, s31, 38
	v_writelane_b32 v254, s88, 39
	s_add_i32 s40, s90, 0xc000
	s_add_i32 s41, s90, 0xe000
	v_writelane_b32 v254, s89, 40
	v_writelane_b32 v254, s29, 41
	v_writelane_b32 v254, s34, 42
	v_writelane_b32 v254, s35, 43
	v_writelane_b32 v254, s17, 44
	v_writelane_b32 v254, s38, 45
	v_writelane_b32 v254, s39, 46
	v_writelane_b32 v254, s18, 47
	v_writelane_b32 v254, s40, 48
	s_add_i32 s43, s90, 0x4000
	v_writelane_b32 v254, s41, 49
	v_mov_b32_e32 v1, v0
	v_mov_b32_e32 v2, v0
	v_mov_b32_e32 v3, v0
	s_movk_i32 s36, 0x3800
	s_mov_b64 s[14:15], 0x1800
	s_movk_i32 s16, 0x1000
	s_movk_i32 s37, 0x1c00
	s_mov_b64 s[96:97], 0x80
	s_movk_i32 s67, 0xe0
	s_movk_i32 s73, 0x60
	s_movk_i32 s74, 0x80
	s_movk_i32 s75, 0xa0
	s_movk_i32 s79, 0xc0
	s_mov_b64 s[92:93], 0x3000
	s_mov_b32 s42, 0x800000
	v_mov_b32_e32 v186, 0xe0
	s_mov_b32 s44, s95
	s_mov_b32 s101, 0
	s_mov_b32 s98, 0
	s_mov_b32 s99, 0x89abcdef
	v_writelane_b32 v254, s43, 50
	s_branch .LBB0_565

; __global__ void __launch_bounds__(NWAVES * 64, 2) fwd(Args args) {
;     ...
;         for (int pi = vcu; pi < 256; pi += G) {
;             const int bh = pi >> 3, tp = pi & 7, b = bh >> 3, h = bh & 7;
;             attn_item<true>(lds, Z, MIX, b, h, 15 - tp, lam, shift, subln, 0, wid, 0);
;             ret_pair(lds, Z, MIX, b, h, 15 - tp, tp, ret_gn + 128 * h, wid);
;             attn_item<true>(lds, Z, MIX, b, h, tp, lam, shift, subln, 0, wid, 0);
;         }
;         __syncthreads();
.LBB0_653:
	s_setprio 0
	v_readlane_b32 s80, v254, 19
	v_readlane_b32 s84, v254, 15
	v_readlane_b32 s88, v254, 12
	v_readlane_b32 s90, v254, 9
	v_readlane_b32 s96, v254, 4
	v_readlane_b32 s77, v254, 18
	v_readlane_b32 s81, v254, 20
	v_readlane_b32 s82, v254, 21
	v_readlane_b32 s83, v254, 22
	v_readlane_b32 s79, v254, 17
	v_readlane_b32 s85, v254, 16
	v_readlane_b32 s86, v254, 14
	v_readlane_b32 s89, v254, 13
	v_readlane_b32 s87, v254, 11
	v_readlane_b32 s91, v254, 10
	v_readlane_b32 s92, v254, 8
	v_readlane_b32 s93, v254, 7
	v_readlane_b32 s94, v254, 6
	v_readlane_b32 s97, v254, 5
	s_waitcnt lgkmcnt(0)
	s_barrier
